# nt (streaming) hint on the read-once f32 input loads: x rows in P0 and the weight-transpose source loads in P0/P5, so they do not evict XB / bf16 weights from L2 / Infinity Cache
# speedup vs baseline: 1.0302x; 1.0169x over previous
; #define LAS __attribute__((address_space(3)))
; __device__ __forceinline__ unsigned cvt_pk_bf16(float lo, float hi) { unsigned r; asm volatile("v_cvt_pk_bf16_f32 %0, %1, %2" : "=v"(r) : "v"(lo), "v"(hi)); return r; }
; #define LDS_WAIT() asm volatile("s_waitcnt lgkmcnt(0)" ::: "memory")
; __device__ __forceinline__ void tr_tile(const float* src, int ldw, const float* ksc, bf16_t* dst, int ldd, LAS float* scr, int lane) {
;     float v[32];
; #pragma unroll
;     for (int i = 0; i < 32; ++i) v[i] = src[(size_t)(2 * i + (lane >> 5)) * ldw + (lane & 31)];
; #pragma unroll
;     for (int i = 0; i < 32; ++i) scr[(2 * i + (lane >> 5)) * 33 + (lane & 31)] = v[i];
;     LDS_WAIT();
;     const int c = lane & 7;
;     f32x4 k0 = (f32x4){1.f, 1.f, 1.f, 1.f}, k1 = k0;
;     if (ksc) { k0 = *(const f32x4*)(ksc + 8 * c); k1 = *(const f32x4*)(ksc + 8 * c + 4); }
; #pragma unroll
;     for (int j = 0; j < 4; ++j) { const int n = (lane >> 3) + 8 * j; const LAS float* s = scr + (8 * c) * 33 + n;
;         u32x4 o; o.x = cvt_pk_bf16(s[0 * 33] * k0[0], s[1 * 33] * k0[1]); o.y = cvt_pk_bf16(s[2 * 33] * k0[2], s[3 * 33] * k0[3]);
;         o.z = cvt_pk_bf16(s[4 * 33] * k1[0], s[5 * 33] * k1[1]); o.w = cvt_pk_bf16(s[6 * 33] * k1[2], s[7 * 33] * k1[3]);
;         *(u32x4*)(dst + (size_t)n * ldd + 8 * c) = o; }
; __global__ void __launch_bounds__(NTHR, 2) hybrid_block_fwd(Args a) {
;     ...
;             {
;                 const int kb = r >> 7, nb = r & 127, n0 = nb * 32, pn = n0 >> 8, bj = (n0 >> 7) & 1, j0 = n0 & 127, k0 = kb * 64;
;                 const float* W = (bj ? w_i : w_a) + (size_t)(pn >> 1) * 65536;
;                 tr_tile(W + (size_t)k0 * 256 + (pn & 1) * 128 + j0, 256, nullptr, WT_GATE + (size_t)n0 * 256 + k0, 256, scr, lane);
;             }
.LBB0_33:
	s_cmpk_gt_i32 s18, 0x23ff
	s_mov_b64 s[8:9], -1
	s_cbranch_scc0 .LBB0_51
	s_cmpk_gt_u32 s18, 0x27ff
	s_cbranch_scc0 .LBB0_48
	s_cmpk_gt_u32 s18, 0x2fff
	s_cbranch_scc0 .LBB0_45
	s_cmpk_gt_u32 s18, 0x37ff
	s_cbranch_scc0 .LBB0_42
	s_cmpk_gt_u32 s18, 0x387f
	v_lshlrev_b32_e32 v89, 2, v8
	v_lshlrev_b32_e32 v91, 2, v12
	v_lshlrev_b32_e32 v93, 2, v16
	v_lshlrev_b32_e32 v95, 2, v20
	v_lshlrev_b32_e32 v97, 2, v24
	v_lshlrev_b32_e32 v99, 2, v28
	v_lshlrev_b32_e32 v101, 2, v32
	v_lshlrev_b32_e32 v103, 2, v36
	v_lshlrev_b32_e32 v105, 2, v40
	v_lshlrev_b32_e32 v107, 2, v44
	v_lshlrev_b32_e32 v109, 2, v48
	v_lshlrev_b32_e32 v111, 2, v52
	v_lshlrev_b32_e32 v113, 2, v56
	v_lshlrev_b32_e32 v115, 2, v60
	v_lshlrev_b32_e32 v117, 2, v64
	v_lshlrev_b32_e32 v119, 2, v68
	v_lshlrev_b32_e32 v121, 2, v72
	v_lshlrev_b32_e32 v123, 2, v76
	v_lshlrev_b32_e32 v125, 2, v80
	v_lshlrev_b32_e32 v127, 2, v84
	v_lshlrev_b32_e32 v129, 2, v88
	v_lshlrev_b32_e32 v131, 2, v92
	v_lshlrev_b32_e32 v133, 2, v96
	v_lshlrev_b32_e32 v135, 2, v100
	v_lshlrev_b32_e32 v139, 2, v104
	v_lshlrev_b32_e32 v141, 2, v108
	v_lshlrev_b32_e32 v143, 2, v112
	v_lshlrev_b32_e32 v145, 2, v116
	v_lshlrev_b32_e32 v147, 2, v120
	v_lshlrev_b32_e32 v149, 2, v124
	v_lshlrev_b32_e32 v151, 2, v128
	v_lshlrev_b32_e32 v153, 2, v132
	v_lshlrev_b32_e32 v6, 1, v152
	v_lshlrev_b32_e32 v4, 1, v140
	v_lshlrev_b32_e32 v2, 1, v144
	v_lshlrev_b32_e32 v0, 1, v148
	s_cbranch_scc0 .LBB0_39
	s_add_i32 s6, s18, 0xffffc780
	s_lshr_b32 s6, s6, 1
	s_and_b32 s10, s5, 0xfe0
	s_and_b32 s11, s5, 0x60
	s_and_b32 s6, s6, 0x7fffffc0
	s_bitcmp0_b32 s18, 2
	s_cselect_b32 s8, s37, s41
	s_cselect_b32 s9, s36, s40
	s_lshl_b32 s19, s5, 9
	s_and_b32 s19, s19, 0x1c0000
	s_add_u32 s19, s9, s19
	s_addc_u32 s20, s8, 0
	s_lshl_b64 s[8:9], s[6:7], 10
	s_add_u32 s8, s19, s8
	s_addc_u32 s9, s20, s9
	s_and_b32 s19, s12, 0x80
	s_lshl_b32 s19, s19, 2
	s_add_u32 s8, s8, s19
	s_addc_u32 s9, s9, 0
	s_lshl_b32 s11, s11, 2
	s_add_u32 s8, s8, s11
	s_addc_u32 s9, s9, 0
	global_load_dword v1, v89, s[8:9] nt
	global_load_dword v3, v91, s[8:9] nt
	global_load_dword v5, v93, s[8:9] nt
	global_load_dword v7, v95, s[8:9] nt
	global_load_dword v136, v97, s[8:9] nt
	global_load_dword v155, v99, s[8:9] nt
	global_load_dword v157, v101, s[8:9] nt
	global_load_dword v160, v103, s[8:9] nt
	global_load_dword v161, v105, s[8:9] nt
	global_load_dword v162, v107, s[8:9] nt
	global_load_dword v163, v109, s[8:9] nt
	global_load_dword v164, v111, s[8:9] nt
	global_load_dword v165, v113, s[8:9] nt
	global_load_dword v166, v115, s[8:9] nt
	global_load_dword v167, v117, s[8:9] nt
	global_load_dword v168, v119, s[8:9] nt
	global_load_dword v169, v121, s[8:9] nt
	global_load_dword v170, v123, s[8:9] nt
	global_load_dword v171, v125, s[8:9] nt
	global_load_dword v172, v127, s[8:9] nt
	global_load_dword v173, v129, s[8:9] nt
	global_load_dword v174, v131, s[8:9] nt
	global_load_dword v175, v133, s[8:9] nt
	global_load_dword v176, v135, s[8:9] nt
	global_load_dword v177, v139, s[8:9] nt
	global_load_dword v178, v141, s[8:9] nt
	global_load_dword v179, v143, s[8:9] nt
	global_load_dword v180, v145, s[8:9] nt
	global_load_dword v181, v147, s[8:9] nt
	global_load_dword v182, v149, s[8:9] nt
	global_load_dword v183, v151, s[8:9] nt
	global_load_dword v184, v153, s[8:9] nt
	v_add_u32_e32 v185, v85, v87
	v_add_u32_e32 v186, v85, v11
	v_add_u32_e32 v187, v85, v13
	v_add_u32_e32 v188, v85, v15
	v_add_u32_e32 v189, v85, v83
	s_lshl_b32 s8, s10, 9
	v_readlane_b32 s2, v248, 30
	v_add_u32_e32 v190, 0x400, v185
	v_add_u32_e32 v191, 0x400, v186
	v_add_u32_e32 v192, 0x400, v187
	v_add_u32_e32 v193, 0x400, v188
	v_add_u32_e32 v194, 0x400, v189
	s_add_u32 s8, s2, s8
	v_readlane_b32 s2, v248, 31
	s_addc_u32 s9, s2, 0
	s_lshl_b32 s6, s6, 1
	s_add_u32 s8, s8, s6
	s_addc_u32 s9, s9, 0
	s_waitcnt vmcnt(30)
	ds_write2_b32 v185, v1, v3 offset1:66
	s_waitcnt vmcnt(28)
	ds_write2_b32 v185, v5, v7 offset0:132 offset1:198
	s_waitcnt vmcnt(26)
	ds_write2_b32 v190, v136, v155 offset0:8 offset1:74
	s_waitcnt vmcnt(24)
	ds_write2_b32 v186, v157, v160 offset1:66
	s_waitcnt vmcnt(22)
	ds_write2_b32 v186, v161, v162 offset0:132 offset1:198
	s_waitcnt vmcnt(20)
	ds_write2_b32 v191, v163, v164 offset0:8 offset1:74
	s_waitcnt vmcnt(18)
	ds_write2_b32 v187, v165, v166 offset1:66
	s_waitcnt vmcnt(16)
	ds_write2_b32 v187, v167, v168 offset0:132 offset1:198
	s_waitcnt vmcnt(14)
	ds_write2_b32 v192, v169, v170 offset0:8 offset1:74
	s_waitcnt vmcnt(12)
	ds_write2_b32 v188, v171, v172 offset1:66
	s_waitcnt vmcnt(10)
	ds_write2_b32 v188, v173, v174 offset0:132 offset1:198
	s_waitcnt vmcnt(8)
	ds_write2_b32 v193, v175, v176 offset0:8 offset1:74
	s_waitcnt vmcnt(6)
	ds_write2_b32 v189, v177, v178 offset1:66
	s_waitcnt vmcnt(4)
	ds_write2_b32 v189, v179, v180 offset0:132 offset1:198
	s_waitcnt vmcnt(2)
	ds_write2_b32 v194, v181, v182 offset0:8 offset1:74
	s_waitcnt vmcnt(0)
	ds_write2_b32 v194, v183, v184 offset0:140 offset1:206
	s_waitcnt lgkmcnt(0)
	ds_read2_b32 v[160:161], v17 offset1:33
	s_waitcnt lgkmcnt(0)
	v_cvt_pk_bf16_f32 v160, v160, v161
	ds_read2_b32 v[162:163], v17 offset0:66 offset1:99
	v_lshlrev_b32_e32 v136, 1, v138
	s_waitcnt lgkmcnt(0)
	v_cvt_pk_bf16_f32 v161, v162, v163
	ds_read2_b32 v[162:163], v17 offset0:132 offset1:165
	v_mov_b32_e32 v7, v137
	v_lshl_add_u64 v[166:167], s[8:9], 0, v[136:137]
	s_waitcnt lgkmcnt(0)
	v_cvt_pk_bf16_f32 v162, v162, v163
	ds_read2_b32 v[164:165], v17 offset0:198 offset1:231
	s_waitcnt lgkmcnt(0)
	v_cvt_pk_bf16_f32 v163, v164, v165
	v_lshl_add_u64 v[168:169], v[166:167], 0, v[6:7]
	ds_read2_b32 v[164:165], v17 offset0:8 offset1:41
	global_store_dwordx4 v[168:169], v[160:163], off
	v_mov_b32_e32 v5, v137
	v_lshl_add_u64 v[168:169], v[166:167], 0, v[4:5]
	s_waitcnt lgkmcnt(0)
; #define LAS __attribute__((address_space(3)))
; __device__ __forceinline__ unsigned cvt_pk_bf16(float lo, float hi) { unsigned r; asm volatile("v_cvt_pk_bf16_f32 %0, %1, %2" : "=v"(r) : "v"(lo), "v"(hi)); return r; }
; __device__ __forceinline__ void tr_tile(const float* src, int ldw, const float* ksc, bf16_t* dst, int ldd, LAS float* scr, int lane) {
;     ...
;     for (int j = 0; j < 4; ++j) { const int n = (lane >> 3) + 8 * j; const LAS float* s = scr + (8 * c) * 33 + n;
;         u32x4 o; o.x = cvt_pk_bf16(s[0 * 33] * k0[0], s[1 * 33] * k0[1]); o.y = cvt_pk_bf16(s[2 * 33] * k0[2], s[3 * 33] * k0[3]);
;         o.z = cvt_pk_bf16(s[4 * 33] * k1[0], s[5 * 33] * k1[1]); o.w = cvt_pk_bf16(s[6 * 33] * k1[2], s[7 * 33] * k1[3]);
;         *(u32x4*)(dst + (size_t)n * ldd + 8 * c) = o; }
	v_cvt_pk_bf16_f32 v160, v164, v165
	ds_read2_b32 v[162:163], v17 offset0:74 offset1:107
	s_waitcnt lgkmcnt(0)
	v_cvt_pk_bf16_f32 v161, v162, v163
	ds_read2_b32 v[162:163], v17 offset0:140 offset1:173
	s_waitcnt lgkmcnt(0)
	v_cvt_pk_bf16_f32 v162, v162, v163
	ds_read2_b32 v[164:165], v17 offset0:206 offset1:239
	s_waitcnt lgkmcnt(0)
	v_cvt_pk_bf16_f32 v163, v164, v165
	ds_read2_b32 v[164:165], v17 offset0:16 offset1:49
	global_store_dwordx4 v[168:169], v[160:163], off
	v_mov_b32_e32 v3, v137
	v_lshl_add_u64 v[168:169], v[166:167], 0, v[2:3]
	s_waitcnt lgkmcnt(0)
	v_cvt_pk_bf16_f32 v160, v164, v165
	ds_read2_b32 v[162:163], v17 offset0:82 offset1:115
	s_waitcnt lgkmcnt(0)
	v_cvt_pk_bf16_f32 v161, v162, v163
	ds_read2_b32 v[162:163], v17 offset0:148 offset1:181
	s_waitcnt lgkmcnt(0)
	v_cvt_pk_bf16_f32 v162, v162, v163
	ds_read2_b32 v[164:165], v17 offset0:214 offset1:247
	s_waitcnt lgkmcnt(0)
	v_cvt_pk_bf16_f32 v163, v164, v165
	ds_read2_b32 v[164:165], v17 offset0:24 offset1:57
	global_store_dwordx4 v[168:169], v[160:163], off
	v_mov_b32_e32 v1, v137
	s_mov_b64 s[8:9], 0
	s_waitcnt lgkmcnt(0)
	v_cvt_pk_bf16_f32 v160, v164, v165
	ds_read2_b32 v[162:163], v17 offset0:90 offset1:123
	s_waitcnt lgkmcnt(0)
	v_cvt_pk_bf16_f32 v161, v162, v163
	ds_read2_b32 v[162:163], v17 offset0:156 offset1:189
	s_waitcnt lgkmcnt(0)
	v_cvt_pk_bf16_f32 v162, v162, v163
	ds_read2_b32 v[164:165], v17 offset0:222 offset1:255
	s_waitcnt lgkmcnt(0)
	v_cvt_pk_bf16_f32 v163, v164, v165
	v_lshl_add_u64 v[164:165], v[166:167], 0, v[0:1]
	global_store_dwordx4 v[164:165], v[160:163], off
	s_waitcnt lgkmcnt(0)
; #define LAS __attribute__((address_space(3)))
; __device__ __forceinline__ unsigned cvt_pk_bf16(float lo, float hi) { unsigned r; asm volatile("v_cvt_pk_bf16_f32 %0, %1, %2" : "=v"(r) : "v"(lo), "v"(hi)); return r; }
; #define LDS_WAIT() asm volatile("s_waitcnt lgkmcnt(0)" ::: "memory")
; __device__ __forceinline__ void tr_tile(const float* src, int ldw, const float* ksc, bf16_t* dst, int ldd, LAS float* scr, int lane) {
;     float v[32];
; #pragma unroll
;     for (int i = 0; i < 32; ++i) v[i] = src[(size_t)(2 * i + (lane >> 5)) * ldw + (lane & 31)];
; #pragma unroll
;     for (int i = 0; i < 32; ++i) scr[(2 * i + (lane >> 5)) * 33 + (lane & 31)] = v[i];
;     LDS_WAIT();
;     const int c = lane & 7;
;     f32x4 k0 = (f32x4){1.f, 1.f, 1.f, 1.f}, k1 = k0;
;     if (ksc) { k0 = *(const f32x4*)(ksc + 8 * c); k1 = *(const f32x4*)(ksc + 8 * c + 4); }
; #pragma unroll
;     for (int j = 0; j < 4; ++j) { const int n = (lane >> 3) + 8 * j; const LAS float* s = scr + (8 * c) * 33 + n;
;         u32x4 o; o.x = cvt_pk_bf16(s[0 * 33] * k0[0], s[1 * 33] * k0[1]); o.y = cvt_pk_bf16(s[2 * 33] * k0[2], s[3 * 33] * k0[3]);
;         o.z = cvt_pk_bf16(s[4 * 33] * k1[0], s[5 * 33] * k1[1]); o.w = cvt_pk_bf16(s[6 * 33] * k1[2], s[7 * 33] * k1[3]);
;         *(u32x4*)(dst + (size_t)n * ldd + 8 * c) = o; }
; __device__ __forceinline__ void tr_plain(const float* W, int K, int N, const float* ksc, bf16_t* WT, int item, LAS float* scr, int lane) {
;     const int nblk = N / 32, kb = item / nblk, nb = item % nblk, k0 = kb * 64, n0 = nb * 32;
;     tr_tile(W + (size_t)k0 * N + n0, N, ksc ? ksc + k0 : nullptr, WT + (size_t)n0 * K + k0, K, scr, lane);
; __global__ void __launch_bounds__(NTHR, 2) hybrid_block_fwd(Args a) {
;     ...
;             if (r < I_POOL) { const int g = r >> 5; tr_plain(w_pool + (size_t)g * 65536, 256, 256, nullptr, WT_POOL + (size_t)g * 65536, r & 31, scr, lane); continue; } r -= I_POOL;
.LBB0_39:
	s_andn2_b64 vcc, exec, s[8:9]
	s_cbranch_vccnz .LBB0_41
	s_add_i32 s6, s18, 0xffffc800
	s_lshr_b32 s6, s6, 5
	s_lshl_b64 s[8:9], s[6:7], 18
	s_add_u32 s10, s60, s8
	s_addc_u32 s11, s61, s9
	s_lshl_b64 s[8:9], s[6:7], 17
	s_add_u32 s6, s16, s8
	s_addc_u32 s19, s25, s9
	s_and_b32 s20, s13, 0xc0
	s_and_b32 s21, s5, 0xe0
	s_lshl_b32 s8, s20, 10
	s_add_u32 s8, s10, s8
	s_addc_u32 s9, s11, 0
	s_lshl_b32 s10, s21, 2
	s_add_u32 s8, s8, s10
	s_addc_u32 s9, s9, 0
	global_load_dword v1, v89, s[8:9] nt
	global_load_dword v3, v91, s[8:9] nt
	global_load_dword v5, v93, s[8:9] nt
	global_load_dword v7, v95, s[8:9] nt
	s_nop 0
	global_load_dword v89, v97, s[8:9] nt
	global_load_dword v91, v99, s[8:9] nt
	global_load_dword v93, v101, s[8:9] nt
	global_load_dword v95, v103, s[8:9] nt
	s_nop 0
	global_load_dword v97, v105, s[8:9] nt
	global_load_dword v99, v107, s[8:9] nt
	global_load_dword v101, v109, s[8:9] nt
	global_load_dword v103, v111, s[8:9] nt
	s_nop 0
	global_load_dword v105, v113, s[8:9] nt
	global_load_dword v107, v115, s[8:9] nt
	global_load_dword v109, v117, s[8:9] nt
	global_load_dword v111, v119, s[8:9] nt
	s_nop 0
	global_load_dword v113, v121, s[8:9] nt
	global_load_dword v115, v123, s[8:9] nt
	global_load_dword v117, v125, s[8:9] nt
	global_load_dword v119, v127, s[8:9] nt
	s_nop 0
	global_load_dword v121, v129, s[8:9] nt
	global_load_dword v123, v131, s[8:9] nt
	global_load_dword v125, v133, s[8:9] nt
	global_load_dword v127, v135, s[8:9] nt
	s_nop 0
	global_load_dword v129, v139, s[8:9] nt
	global_load_dword v131, v141, s[8:9] nt
	global_load_dword v133, v143, s[8:9] nt
	global_load_dword v135, v145, s[8:9] nt
	global_load_dword v136, v147, s[8:9] nt
	s_nop 0
	global_load_dword v139, v149, s[8:9] nt
	global_load_dword v141, v151, s[8:9] nt
	global_load_dword v143, v153, s[8:9] nt
	v_add_u32_e32 v145, v85, v87
	v_add_u32_e32 v147, v85, v11
	v_add_u32_e32 v149, v85, v13
	v_add_u32_e32 v151, v85, v15
	v_add_u32_e32 v153, v85, v83
	s_lshl_b32 s8, s21, 9
	v_add_u32_e32 v155, 0x400, v145
	v_add_u32_e32 v157, 0x400, v147
	v_add_u32_e32 v160, 0x400, v149
	v_add_u32_e32 v161, 0x400, v151
	v_add_u32_e32 v162, 0x400, v153
	s_add_u32 s6, s6, s8
	s_addc_u32 s9, s19, 0
	s_lshl_b32 s8, s20, 1
	s_add_u32 s8, s6, s8
	s_addc_u32 s9, s9, 0
	s_waitcnt vmcnt(30)
	ds_write2_b32 v145, v1, v3 offset1:66
	s_waitcnt vmcnt(28)
	ds_write2_b32 v145, v5, v7 offset0:132 offset1:198
	s_waitcnt vmcnt(26)
	ds_write2_b32 v155, v89, v91 offset0:8 offset1:74
	s_waitcnt vmcnt(24)
	ds_write2_b32 v147, v93, v95 offset1:66
	s_waitcnt vmcnt(22)
	ds_write2_b32 v147, v97, v99 offset0:132 offset1:198
	s_waitcnt vmcnt(20)
	ds_write2_b32 v157, v101, v103 offset0:8 offset1:74
	s_waitcnt vmcnt(18)
	ds_write2_b32 v149, v105, v107 offset1:66
	s_waitcnt vmcnt(16)
	ds_write2_b32 v149, v109, v111 offset0:132 offset1:198
	s_waitcnt vmcnt(14)
	ds_write2_b32 v160, v113, v115 offset0:8 offset1:74
	s_waitcnt vmcnt(12)
	ds_write2_b32 v151, v117, v119 offset1:66
	s_waitcnt vmcnt(10)
	ds_write2_b32 v151, v121, v123 offset0:132 offset1:198
	s_waitcnt vmcnt(8)
	ds_write2_b32 v161, v125, v127 offset0:8 offset1:74
	s_waitcnt vmcnt(6)
	ds_write2_b32 v153, v129, v131 offset1:66
	s_waitcnt vmcnt(4)
	ds_write2_b32 v153, v133, v135 offset0:132 offset1:198
	s_waitcnt vmcnt(2)
	ds_write2_b32 v162, v136, v139 offset0:8 offset1:74
	s_waitcnt vmcnt(0)
	ds_write2_b32 v162, v141, v143 offset0:140 offset1:206
	s_waitcnt lgkmcnt(0)
	ds_read2_b32 v[160:161], v17 offset1:33
	s_waitcnt lgkmcnt(0)
	v_cvt_pk_bf16_f32 v160, v160, v161
	ds_read2_b32 v[162:163], v17 offset0:66 offset1:99
	v_lshlrev_b32_e32 v136, 1, v138
	s_waitcnt lgkmcnt(0)
	v_cvt_pk_bf16_f32 v161, v162, v163
	ds_read2_b32 v[162:163], v17 offset0:132 offset1:165
	v_mov_b32_e32 v7, v137
	v_lshl_add_u64 v[166:167], s[8:9], 0, v[136:137]
	s_waitcnt lgkmcnt(0)
	v_cvt_pk_bf16_f32 v162, v162, v163
	ds_read2_b32 v[164:165], v17 offset0:198 offset1:231
	v_lshl_add_u64 v[6:7], v[166:167], 0, v[6:7]
	s_waitcnt lgkmcnt(0)
	v_cvt_pk_bf16_f32 v163, v164, v165
	ds_read2_b32 v[164:165], v17 offset0:8 offset1:41
	global_store_dwordx4 v[6:7], v[160:163], off
	v_mov_b32_e32 v5, v137
	v_lshl_add_u64 v[4:5], v[166:167], 0, v[4:5]
	s_waitcnt lgkmcnt(0)
	v_cvt_pk_bf16_f32 v160, v164, v165
	ds_read2_b32 v[6:7], v17 offset0:74 offset1:107
	s_waitcnt lgkmcnt(0)
	v_cvt_pk_bf16_f32 v161, v6, v7
	ds_read2_b32 v[6:7], v17 offset0:140 offset1:173
	s_waitcnt lgkmcnt(0)
	v_cvt_pk_bf16_f32 v162, v6, v7
	ds_read2_b32 v[6:7], v17 offset0:206 offset1:239
	s_waitcnt lgkmcnt(0)
	v_cvt_pk_bf16_f32 v163, v6, v7
	ds_read2_b32 v[6:7], v17 offset0:16 offset1:49
	global_store_dwordx4 v[4:5], v[160:163], off
	s_waitcnt lgkmcnt(0)
	v_cvt_pk_bf16_f32 v4, v6, v7
	ds_read2_b32 v[6:7], v17 offset0:82 offset1:115
	s_waitcnt lgkmcnt(0)
	v_cvt_pk_bf16_f32 v5, v6, v7
	ds_read2_b32 v[6:7], v17 offset0:148 offset1:181
	v_mov_b32_e32 v3, v137
	s_waitcnt lgkmcnt(0)
	v_cvt_pk_bf16_f32 v6, v6, v7
	ds_read2_b32 v[160:161], v17 offset0:214 offset1:247
	v_lshl_add_u64 v[2:3], v[166:167], 0, v[2:3]
	s_waitcnt lgkmcnt(0)
	v_cvt_pk_bf16_f32 v7, v160, v161
	ds_read2_b32 v[160:161], v17 offset0:24 offset1:57
	global_store_dwordx4 v[2:3], v[4:7], off
	s_waitcnt lgkmcnt(0)
	v_cvt_pk_bf16_f32 v2, v160, v161
	ds_read2_b32 v[4:5], v17 offset0:90 offset1:123
	v_mov_b32_e32 v1, v137
	s_waitcnt lgkmcnt(0)
	v_cvt_pk_bf16_f32 v3, v4, v5
	ds_read2_b32 v[4:5], v17 offset0:156 offset1:189
	v_lshl_add_u64 v[0:1], v[166:167], 0, v[0:1]
	s_waitcnt lgkmcnt(0)
	v_cvt_pk_bf16_f32 v4, v4, v5
	ds_read2_b32 v[6:7], v17 offset0:222 offset1:255
	s_waitcnt lgkmcnt(0)
	v_cvt_pk_bf16_f32 v5, v6, v7
	global_store_dwordx4 v[0:1], v[2:5], off
	s_waitcnt lgkmcnt(0)

; #define LAS __attribute__((address_space(3)))
; __device__ __forceinline__ unsigned cvt_pk_bf16(float lo, float hi) { unsigned r; asm volatile("v_cvt_pk_bf16_f32 %0, %1, %2" : "=v"(r) : "v"(lo), "v"(hi)); return r; }
; #define LDS_WAIT() asm volatile("s_waitcnt lgkmcnt(0)" ::: "memory")
; __device__ __forceinline__ void tr_tile(const float* src, int ldw, const float* ksc, bf16_t* dst, int ldd, LAS float* scr, int lane) {
;     float v[32];
; #pragma unroll
;     for (int i = 0; i < 32; ++i) v[i] = src[(size_t)(2 * i + (lane >> 5)) * ldw + (lane & 31)];
; #pragma unroll
;     for (int i = 0; i < 32; ++i) scr[(2 * i + (lane >> 5)) * 33 + (lane & 31)] = v[i];
;     LDS_WAIT();
;     const int c = lane & 7;
;     f32x4 k0 = (f32x4){1.f, 1.f, 1.f, 1.f}, k1 = k0;
;     if (ksc) { k0 = *(const f32x4*)(ksc + 8 * c); k1 = *(const f32x4*)(ksc + 8 * c + 4); }
; #pragma unroll
;     for (int j = 0; j < 4; ++j) { const int n = (lane >> 3) + 8 * j; const LAS float* s = scr + (8 * c) * 33 + n;
;         u32x4 o; o.x = cvt_pk_bf16(s[0 * 33] * k0[0], s[1 * 33] * k0[1]); o.y = cvt_pk_bf16(s[2 * 33] * k0[2], s[3 * 33] * k0[3]);
;         o.z = cvt_pk_bf16(s[4 * 33] * k1[0], s[5 * 33] * k1[1]); o.w = cvt_pk_bf16(s[6 * 33] * k1[2], s[7 * 33] * k1[3]);
;         *(u32x4*)(dst + (size_t)n * ldd + 8 * c) = o; }
; __device__ __forceinline__ void tr_plain(const float* W, int K, int N, const float* ksc, bf16_t* WT, int item, LAS float* scr, int lane) {
;     const int nblk = N / 32, kb = item / nblk, nb = item % nblk, k0 = kb * 64, n0 = nb * 32;
;     tr_tile(W + (size_t)k0 * N + n0, N, ksc ? ksc + k0 : nullptr, WT + (size_t)n0 * K + k0, K, scr, lane);
; __global__ void __launch_bounds__(NTHR, 2) hybrid_block_fwd(Args a) {
;     ...
;             if (r < I_OUT) { tr_plain(w_out, D, D, nullptr, WT_OUT, r, scr, lane); continue; } r -= I_OUT;
.LBB0_42:
	s_andn2_b64 vcc, exec, s[8:9]
	s_cbranch_vccnz .LBB0_44
	s_add_i32 s6, s18, 0xd000
	s_and_b32 s6, s6, 0xffc0
	s_and_b32 s10, s5, 0x7e0
	s_lshl_b32 s8, s6, 13
	s_add_u32 s8, s50, s8
	s_addc_u32 s9, s51, 0
	s_lshl_b32 s11, s10, 2
	s_add_u32 s8, s8, s11
	s_addc_u32 s9, s9, 0
	v_lshlrev_b32_e32 v0, 2, v10
	v_lshlrev_b32_e32 v1, 2, v14
	v_lshlrev_b32_e32 v2, 2, v18
	v_lshlrev_b32_e32 v3, 2, v22
	v_lshlrev_b32_e32 v4, 2, v26
	v_lshlrev_b32_e32 v5, 2, v30
	v_lshlrev_b32_e32 v6, 2, v34
	v_lshlrev_b32_e32 v7, 2, v38
	v_lshlrev_b32_e32 v89, 2, v42
	v_lshlrev_b32_e32 v91, 2, v46
	v_lshlrev_b32_e32 v93, 2, v50
	v_lshlrev_b32_e32 v95, 2, v54
	v_lshlrev_b32_e32 v97, 2, v58
	v_lshlrev_b32_e32 v99, 2, v62
	v_lshlrev_b32_e32 v101, 2, v66
	v_lshlrev_b32_e32 v103, 2, v70
	global_load_dword v0, v0, s[8:9] nt
	s_nop 0
	global_load_dword v1, v1, s[8:9] nt
	s_nop 0
	global_load_dword v2, v2, s[8:9] nt
	s_nop 0
	global_load_dword v3, v3, s[8:9] nt
	s_nop 0
	global_load_dword v4, v4, s[8:9] nt
	s_nop 0
	global_load_dword v5, v5, s[8:9] nt
	s_nop 0
	global_load_dword v6, v6, s[8:9] nt
	s_nop 0
	global_load_dword v7, v7, s[8:9] nt
	s_nop 0
	global_load_dword v89, v89, s[8:9] nt
	s_nop 0
	global_load_dword v91, v91, s[8:9] nt
	s_nop 0
	global_load_dword v93, v93, s[8:9] nt
	s_nop 0
	global_load_dword v95, v95, s[8:9] nt
	s_nop 0
	global_load_dword v97, v97, s[8:9] nt
	s_nop 0
	global_load_dword v99, v99, s[8:9] nt
	s_nop 0
	global_load_dword v101, v101, s[8:9] nt
	s_nop 0
	global_load_dword v103, v103, s[8:9] nt
	v_lshlrev_b32_e32 v105, 2, v74
	v_lshlrev_b32_e32 v107, 2, v78
	v_lshlrev_b32_e32 v109, 2, v82
	v_lshlrev_b32_e32 v111, 2, v86
	v_lshlrev_b32_e32 v113, 2, v90
	v_lshlrev_b32_e32 v115, 2, v94
	v_lshlrev_b32_e32 v117, 2, v98
	v_lshlrev_b32_e32 v119, 2, v102
	global_load_dword v105, v105, s[8:9] nt
	s_nop 0
	global_load_dword v107, v107, s[8:9] nt
	s_nop 0
	global_load_dword v109, v109, s[8:9] nt
	s_nop 0
	global_load_dword v111, v111, s[8:9] nt
	s_nop 0
	global_load_dword v113, v113, s[8:9] nt
	s_nop 0
	global_load_dword v115, v115, s[8:9] nt
	s_nop 0
	global_load_dword v117, v117, s[8:9] nt
	s_nop 0
	global_load_dword v119, v119, s[8:9] nt
	v_lshlrev_b32_e32 v121, 2, v106
	v_lshlrev_b32_e32 v123, 2, v110
	v_lshlrev_b32_e32 v125, 2, v114
	v_lshlrev_b32_e32 v127, 2, v118
	v_lshlrev_b32_e32 v129, 2, v122
	v_lshlrev_b32_e32 v131, 2, v126
	v_lshlrev_b32_e32 v133, 2, v130
	v_lshlrev_b32_e32 v135, 2, v134
	global_load_dword v121, v121, s[8:9] nt
	s_nop 0
	global_load_dword v123, v123, s[8:9] nt
	s_nop 0
	global_load_dword v125, v125, s[8:9] nt
	s_nop 0
	global_load_dword v127, v127, s[8:9] nt
	s_nop 0
	global_load_dword v129, v129, s[8:9] nt
	s_nop 0
	global_load_dword v131, v131, s[8:9] nt
	s_nop 0
	global_load_dword v133, v133, s[8:9] nt
	s_nop 0
	global_load_dword v135, v135, s[8:9] nt
	v_add_u32_e32 v136, v85, v87
	v_add_u32_e32 v139, v85, v11
	v_add_u32_e32 v141, v85, v13
	v_add_u32_e32 v143, 0x400, v136
	v_add_u32_e32 v145, 0x400, v139
	v_add_u32_e32 v147, 0x400, v141
	s_lshl_b32 s8, s10, 12
	v_readlane_b32 s2, v248, 34
	s_add_u32 s8, s2, s8
	v_readlane_b32 s2, v248, 35
	s_addc_u32 s9, s2, 0
	s_lshl_b32 s6, s6, 1
	s_add_u32 s8, s8, s6
	s_addc_u32 s9, s9, 0
	s_waitcnt vmcnt(30)
	ds_write2_b32 v136, v0, v1 offset1:66
	s_waitcnt vmcnt(28)
	ds_write2_b32 v136, v2, v3 offset0:132 offset1:198
	s_waitcnt vmcnt(26)
	ds_write2_b32 v143, v4, v5 offset0:8 offset1:74
	s_waitcnt vmcnt(24)
	ds_write2_b32 v139, v6, v7 offset1:66
	s_waitcnt vmcnt(22)
	ds_write2_b32 v139, v89, v91 offset0:132 offset1:198
	s_waitcnt vmcnt(20)
	ds_write2_b32 v145, v93, v95 offset0:8 offset1:74
	s_waitcnt vmcnt(18)
	ds_write2_b32 v141, v97, v99 offset1:66
	s_waitcnt vmcnt(16)
	ds_write2_b32 v141, v101, v103 offset0:132 offset1:198
	s_waitcnt vmcnt(14)
	ds_write2_b32 v147, v105, v107 offset0:8 offset1:74
	v_add_u32_e32 v0, v85, v15
	s_waitcnt vmcnt(12)
	ds_write2_b32 v0, v109, v111 offset1:66
	s_waitcnt vmcnt(10)
	ds_write2_b32 v0, v113, v115 offset0:132 offset1:198
	v_add_u32_e32 v0, 0x400, v0
	s_waitcnt vmcnt(8)
	ds_write2_b32 v0, v117, v119 offset0:8 offset1:74
	v_add_u32_e32 v0, v85, v83
	s_waitcnt vmcnt(6)
	ds_write2_b32 v0, v121, v123 offset1:66
	s_waitcnt vmcnt(4)
	ds_write2_b32 v0, v125, v127 offset0:132 offset1:198
	v_add_u32_e32 v0, 0x400, v0
	s_waitcnt vmcnt(2)
	ds_write2_b32 v0, v129, v131 offset0:8 offset1:74
	s_waitcnt vmcnt(0)
	ds_write2_b32 v0, v133, v135 offset0:140 offset1:206
	s_waitcnt lgkmcnt(0)
	ds_read2_b32 v[0:1], v17 offset1:33
	s_waitcnt lgkmcnt(0)
	v_cvt_pk_bf16_f32 v0, v0, v1
	ds_read2_b32 v[2:3], v17 offset0:66 offset1:99
	v_lshlrev_b32_e32 v136, 1, v138
	s_waitcnt lgkmcnt(0)
	v_cvt_pk_bf16_f32 v1, v2, v3
	ds_read2_b32 v[2:3], v17 offset0:132 offset1:165
	v_lshl_add_u64 v[6:7], s[8:9], 0, v[136:137]
	v_lshlrev_b32_e32 v136, 1, v154
	s_waitcnt lgkmcnt(0)
	v_cvt_pk_bf16_f32 v2, v2, v3
	ds_read2_b32 v[4:5], v17 offset0:198 offset1:231
	s_waitcnt lgkmcnt(0)
	v_cvt_pk_bf16_f32 v3, v4, v5
	v_lshl_add_u64 v[160:161], v[6:7], 0, v[136:137]
	ds_read2_b32 v[4:5], v17 offset0:8 offset1:41
	global_store_dwordx4 v[160:161], v[0:3], off
	v_lshlrev_b32_e32 v136, 1, v142
	v_lshl_add_u64 v[160:161], v[6:7], 0, v[136:137]
	s_waitcnt lgkmcnt(0)
	v_cvt_pk_bf16_f32 v0, v4, v5
	ds_read2_b32 v[2:3], v17 offset0:74 offset1:107
	s_waitcnt lgkmcnt(0)
	v_cvt_pk_bf16_f32 v1, v2, v3
	ds_read2_b32 v[2:3], v17 offset0:140 offset1:173
	s_waitcnt lgkmcnt(0)
	v_cvt_pk_bf16_f32 v2, v2, v3
	ds_read2_b32 v[4:5], v17 offset0:206 offset1:239
	s_waitcnt lgkmcnt(0)
	v_cvt_pk_bf16_f32 v3, v4, v5
	ds_read2_b32 v[4:5], v17 offset0:16 offset1:49
	global_store_dwordx4 v[160:161], v[0:3], off
	v_lshlrev_b32_e32 v136, 1, v146
	v_lshl_add_u64 v[160:161], v[6:7], 0, v[136:137]
	s_waitcnt lgkmcnt(0)
	v_cvt_pk_bf16_f32 v0, v4, v5
	ds_read2_b32 v[2:3], v17 offset0:82 offset1:115
	s_waitcnt lgkmcnt(0)
	v_cvt_pk_bf16_f32 v1, v2, v3
	ds_read2_b32 v[2:3], v17 offset0:148 offset1:181
	s_waitcnt lgkmcnt(0)
	v_cvt_pk_bf16_f32 v2, v2, v3
	ds_read2_b32 v[4:5], v17 offset0:214 offset1:247
	s_waitcnt lgkmcnt(0)
	v_cvt_pk_bf16_f32 v3, v4, v5
	ds_read2_b32 v[4:5], v17 offset0:24 offset1:57
	global_store_dwordx4 v[160:161], v[0:3], off
	v_lshlrev_b32_e32 v136, 1, v150
	s_waitcnt lgkmcnt(0)
	v_cvt_pk_bf16_f32 v0, v4, v5
	ds_read2_b32 v[2:3], v17 offset0:90 offset1:123
	s_waitcnt lgkmcnt(0)
	v_cvt_pk_bf16_f32 v1, v2, v3
	ds_read2_b32 v[2:3], v17 offset0:156 offset1:189
	s_waitcnt lgkmcnt(0)
	v_cvt_pk_bf16_f32 v2, v2, v3
	ds_read2_b32 v[4:5], v17 offset0:222 offset1:255
	s_waitcnt lgkmcnt(0)
	v_cvt_pk_bf16_f32 v3, v4, v5
	v_lshl_add_u64 v[4:5], v[6:7], 0, v[136:137]
	global_store_dwordx4 v[4:5], v[0:3], off
	s_waitcnt lgkmcnt(0)

; #define LAS __attribute__((address_space(3)))
; __device__ __forceinline__ unsigned cvt_pk_bf16(float lo, float hi) { unsigned r; asm volatile("v_cvt_pk_bf16_f32 %0, %1, %2" : "=v"(r) : "v"(lo), "v"(hi)); return r; }
; #define LDS_WAIT() asm volatile("s_waitcnt lgkmcnt(0)" ::: "memory")
; __device__ __forceinline__ void tr_tile(const float* src, int ldw, const float* ksc, bf16_t* dst, int ldd, LAS float* scr, int lane) {
;     float v[32];
; #pragma unroll
;     for (int i = 0; i < 32; ++i) v[i] = src[(size_t)(2 * i + (lane >> 5)) * ldw + (lane & 31)];
; #pragma unroll
;     for (int i = 0; i < 32; ++i) scr[(2 * i + (lane >> 5)) * 33 + (lane & 31)] = v[i];
;     LDS_WAIT();
;     const int c = lane & 7;
;     f32x4 k0 = (f32x4){1.f, 1.f, 1.f, 1.f}, k1 = k0;
;     if (ksc) { k0 = *(const f32x4*)(ksc + 8 * c); k1 = *(const f32x4*)(ksc + 8 * c + 4); }
; #pragma unroll
;     for (int j = 0; j < 4; ++j) { const int n = (lane >> 3) + 8 * j; const LAS float* s = scr + (8 * c) * 33 + n;
;         u32x4 o; o.x = cvt_pk_bf16(s[0 * 33] * k0[0], s[1 * 33] * k0[1]); o.y = cvt_pk_bf16(s[2 * 33] * k0[2], s[3 * 33] * k0[3]);
;         o.z = cvt_pk_bf16(s[4 * 33] * k1[0], s[5 * 33] * k1[1]); o.w = cvt_pk_bf16(s[6 * 33] * k1[2], s[7 * 33] * k1[3]);
;         *(u32x4*)(dst + (size_t)n * ldd + 8 * c) = o; }
; __global__ void __launch_bounds__(NTHR, 2) hybrid_block_fwd(Args a) {
;     ...
;             if (r < I_LP) { const int kb = r / (D / 32), nb = r % (D / 32); tr_tile(w_lru_proj + (size_t)kb * 64 * D + nb * 32, D, nullptr, WT_CAT + (size_t)nb * 32 * KC + PW + kb * 64, KC, scr, lane); continue; } r -= I_LP;
.LBB0_45:
	s_andn2_b64 vcc, exec, s[8:9]
	s_cbranch_vccnz .LBB0_47
	s_and_b32 s6, s18, 0x3fc0
	s_addk_i32 s6, 0xd800
	s_and_b32 s10, s18, 63
	s_lshl_b64 s[8:9], s[6:7], 13
	s_add_u32 s8, s48, s8
	s_addc_u32 s9, s49, s9
	s_lshl_b32 s11, s10, 7
	s_add_u32 s8, s8, s11
	s_addc_u32 s9, s9, 0
	v_lshlrev_b32_e32 v0, 2, v10
	v_lshlrev_b32_e32 v1, 2, v14
	v_lshlrev_b32_e32 v2, 2, v18
	v_lshlrev_b32_e32 v3, 2, v22
	v_lshlrev_b32_e32 v4, 2, v26
	v_lshlrev_b32_e32 v5, 2, v30
	v_lshlrev_b32_e32 v6, 2, v34
	v_lshlrev_b32_e32 v7, 2, v38
	v_lshlrev_b32_e32 v89, 2, v42
	v_lshlrev_b32_e32 v91, 2, v46
	v_lshlrev_b32_e32 v93, 2, v50
	v_lshlrev_b32_e32 v95, 2, v54
	v_lshlrev_b32_e32 v97, 2, v58
	v_lshlrev_b32_e32 v99, 2, v62
	v_lshlrev_b32_e32 v101, 2, v66
	v_lshlrev_b32_e32 v103, 2, v70
	global_load_dword v0, v0, s[8:9] nt
	s_nop 0
	global_load_dword v1, v1, s[8:9] nt
	s_nop 0
	global_load_dword v2, v2, s[8:9] nt
	s_nop 0
	global_load_dword v3, v3, s[8:9] nt
	s_nop 0
	global_load_dword v4, v4, s[8:9] nt
	s_nop 0
	global_load_dword v5, v5, s[8:9] nt
	s_nop 0
	global_load_dword v6, v6, s[8:9] nt
	s_nop 0
	global_load_dword v7, v7, s[8:9] nt
	s_nop 0
	global_load_dword v89, v89, s[8:9] nt
	s_nop 0
	global_load_dword v91, v91, s[8:9] nt
	s_nop 0
	global_load_dword v93, v93, s[8:9] nt
	s_nop 0
	global_load_dword v95, v95, s[8:9] nt
	s_nop 0
	global_load_dword v97, v97, s[8:9] nt
	s_nop 0
	global_load_dword v99, v99, s[8:9] nt
	s_nop 0
	global_load_dword v101, v101, s[8:9] nt
	s_nop 0
	global_load_dword v103, v103, s[8:9] nt
	v_lshlrev_b32_e32 v105, 2, v74
	v_lshlrev_b32_e32 v107, 2, v78
	v_lshlrev_b32_e32 v109, 2, v82
	v_lshlrev_b32_e32 v111, 2, v86
	v_lshlrev_b32_e32 v113, 2, v90
	v_lshlrev_b32_e32 v115, 2, v94
	v_lshlrev_b32_e32 v117, 2, v98
	v_lshlrev_b32_e32 v119, 2, v102
	global_load_dword v105, v105, s[8:9] nt
	s_nop 0
	global_load_dword v107, v107, s[8:9] nt
	s_nop 0
	global_load_dword v109, v109, s[8:9] nt
	s_nop 0
	global_load_dword v111, v111, s[8:9] nt
	s_nop 0
	global_load_dword v113, v113, s[8:9] nt
	s_nop 0
	global_load_dword v115, v115, s[8:9] nt
	s_nop 0
	global_load_dword v117, v117, s[8:9] nt
	s_nop 0
	global_load_dword v119, v119, s[8:9] nt
	v_lshlrev_b32_e32 v121, 2, v106
	v_lshlrev_b32_e32 v123, 2, v110
	v_lshlrev_b32_e32 v125, 2, v114
	v_lshlrev_b32_e32 v127, 2, v118
	v_lshlrev_b32_e32 v129, 2, v122
	v_lshlrev_b32_e32 v131, 2, v126
	v_lshlrev_b32_e32 v133, 2, v130
	v_lshlrev_b32_e32 v135, 2, v134
	global_load_dword v121, v121, s[8:9] nt
	s_nop 0
	global_load_dword v123, v123, s[8:9] nt
	s_nop 0
	global_load_dword v125, v125, s[8:9] nt
	s_nop 0
	global_load_dword v127, v127, s[8:9] nt
	s_nop 0
	global_load_dword v129, v129, s[8:9] nt
	s_nop 0
	global_load_dword v131, v131, s[8:9] nt
	s_nop 0
	global_load_dword v133, v133, s[8:9] nt
	s_nop 0
	global_load_dword v135, v135, s[8:9] nt
	v_add_u32_e32 v136, v85, v87
	v_add_u32_e32 v139, v85, v11
	v_add_u32_e32 v141, v85, v13
	v_add_u32_e32 v143, 0x400, v136
	v_add_u32_e32 v145, 0x400, v139
	v_add_u32_e32 v147, 0x400, v141
	s_mul_i32 s10, s10, 0x30000
	v_readlane_b32 s2, v248, 32
	s_add_u32 s10, s2, s10
	v_readlane_b32 s2, v248, 33
	s_addc_u32 s11, s2, 0
	s_lshl_b64 s[8:9], s[6:7], 1
	s_add_u32 s8, s10, s8
	s_addc_u32 s9, s11, s9
	s_waitcnt vmcnt(30)
	ds_write2_b32 v136, v0, v1 offset1:66
	s_waitcnt vmcnt(28)
	ds_write2_b32 v136, v2, v3 offset0:132 offset1:198
	s_waitcnt vmcnt(26)
	ds_write2_b32 v143, v4, v5 offset0:8 offset1:74
	s_waitcnt vmcnt(24)
	ds_write2_b32 v139, v6, v7 offset1:66
	s_waitcnt vmcnt(22)
	ds_write2_b32 v139, v89, v91 offset0:132 offset1:198
	s_waitcnt vmcnt(20)
	ds_write2_b32 v145, v93, v95 offset0:8 offset1:74
	s_waitcnt vmcnt(18)
	ds_write2_b32 v141, v97, v99 offset1:66
	s_waitcnt vmcnt(16)
	ds_write2_b32 v141, v101, v103 offset0:132 offset1:198
	s_waitcnt vmcnt(14)
	ds_write2_b32 v147, v105, v107 offset0:8 offset1:74
	v_add_u32_e32 v0, v85, v15
	s_waitcnt vmcnt(12)
	ds_write2_b32 v0, v109, v111 offset1:66
	s_waitcnt vmcnt(10)
	ds_write2_b32 v0, v113, v115 offset0:132 offset1:198
	v_add_u32_e32 v0, 0x400, v0
	s_waitcnt vmcnt(8)
	ds_write2_b32 v0, v117, v119 offset0:8 offset1:74
	v_add_u32_e32 v0, v85, v83
	s_waitcnt vmcnt(6)
	ds_write2_b32 v0, v121, v123 offset1:66
	s_waitcnt vmcnt(4)
	ds_write2_b32 v0, v125, v127 offset0:132 offset1:198
	v_add_u32_e32 v0, 0x400, v0
	s_waitcnt vmcnt(2)
	ds_write2_b32 v0, v129, v131 offset0:8 offset1:74
	s_waitcnt vmcnt(0)
	ds_write2_b32 v0, v133, v135 offset0:140 offset1:206
	s_waitcnt lgkmcnt(0)
	ds_read2_b32 v[0:1], v17 offset1:33
	s_waitcnt lgkmcnt(0)
	v_cvt_pk_bf16_f32 v0, v0, v1
	ds_read2_b32 v[2:3], v17 offset0:66 offset1:99
	v_lshlrev_b32_e32 v136, 1, v138
	s_waitcnt lgkmcnt(0)
	v_cvt_pk_bf16_f32 v1, v2, v3
	ds_read2_b32 v[2:3], v17 offset0:132 offset1:165
	v_lshl_add_u64 v[6:7], s[8:9], 0, v[136:137]
	v_lshlrev_b32_e32 v136, 1, v156
	s_waitcnt lgkmcnt(0)
	v_cvt_pk_bf16_f32 v2, v2, v3
	ds_read2_b32 v[4:5], v17 offset0:198 offset1:231
	s_waitcnt lgkmcnt(0)
	v_cvt_pk_bf16_f32 v3, v4, v5
	v_lshl_add_u64 v[6:7], v[6:7], 0, v[136:137]
	ds_read2_b32 v[4:5], v17 offset0:8 offset1:41
	global_store_dwordx4 v[6:7], v[0:3], off offset:2048
	v_add_co_u32_e32 v160, vcc, s14, v6
	s_waitcnt lgkmcnt(0)
	v_cvt_pk_bf16_f32 v0, v4, v5
	ds_read2_b32 v[2:3], v17 offset0:74 offset1:107
	s_waitcnt lgkmcnt(0)
	v_cvt_pk_bf16_f32 v1, v2, v3
	ds_read2_b32 v[2:3], v17 offset0:140 offset1:173
	s_waitcnt lgkmcnt(0)
	v_cvt_pk_bf16_f32 v2, v2, v3
	ds_read2_b32 v[4:5], v17 offset0:206 offset1:239
	s_waitcnt lgkmcnt(0)
	v_cvt_pk_bf16_f32 v3, v4, v5
	v_addc_co_u32_e32 v161, vcc, 0, v7, vcc
	ds_read2_b32 v[4:5], v17 offset0:16 offset1:49
	global_store_dwordx4 v[160:161], v[0:3], off offset:2048
	v_add_co_u32_e32 v160, vcc, s15, v6
	s_waitcnt lgkmcnt(0)
	v_cvt_pk_bf16_f32 v0, v4, v5
	ds_read2_b32 v[2:3], v17 offset0:82 offset1:115
	s_waitcnt lgkmcnt(0)
	v_cvt_pk_bf16_f32 v1, v2, v3
	ds_read2_b32 v[2:3], v17 offset0:148 offset1:181
	s_waitcnt lgkmcnt(0)
	v_cvt_pk_bf16_f32 v2, v2, v3
	ds_read2_b32 v[4:5], v17 offset0:214 offset1:247
	s_waitcnt lgkmcnt(0)
	v_cvt_pk_bf16_f32 v3, v4, v5
	v_addc_co_u32_e32 v161, vcc, 0, v7, vcc
	ds_read2_b32 v[4:5], v17 offset0:24 offset1:57
	global_store_dwordx4 v[160:161], v[0:3], off offset:2048
	v_add_co_u32_e32 v6, vcc, 0x24000, v6
	s_waitcnt lgkmcnt(0)
	v_cvt_pk_bf16_f32 v0, v4, v5
	ds_read2_b32 v[2:3], v17 offset0:90 offset1:123
	s_waitcnt lgkmcnt(0)
	v_cvt_pk_bf16_f32 v1, v2, v3
	ds_read2_b32 v[2:3], v17 offset0:156 offset1:189
	v_addc_co_u32_e32 v7, vcc, 0, v7, vcc
	s_waitcnt lgkmcnt(0)
	v_cvt_pk_bf16_f32 v2, v2, v3
	ds_read2_b32 v[4:5], v17 offset0:222 offset1:255
	s_waitcnt lgkmcnt(0)
	v_cvt_pk_bf16_f32 v3, v4, v5
	global_store_dwordx4 v[6:7], v[0:3], off offset:2048
	s_waitcnt lgkmcnt(0)

; #define LAS __attribute__((address_space(3)))
; __device__ __forceinline__ unsigned cvt_pk_bf16(float lo, float hi) { unsigned r; asm volatile("v_cvt_pk_bf16_f32 %0, %1, %2" : "=v"(r) : "v"(lo), "v"(hi)); return r; }
; #define LDS_WAIT() asm volatile("s_waitcnt lgkmcnt(0)" ::: "memory")
; __device__ __forceinline__ void tr_tile(const float* src, int ldw, const float* ksc, bf16_t* dst, int ldd, LAS float* scr, int lane) {
;     float v[32];
; #pragma unroll
;     for (int i = 0; i < 32; ++i) v[i] = src[(size_t)(2 * i + (lane >> 5)) * ldw + (lane & 31)];
; #pragma unroll
;     for (int i = 0; i < 32; ++i) scr[(2 * i + (lane >> 5)) * 33 + (lane & 31)] = v[i];
;     LDS_WAIT();
;     const int c = lane & 7;
;     f32x4 k0 = (f32x4){1.f, 1.f, 1.f, 1.f}, k1 = k0;
;     if (ksc) { k0 = *(const f32x4*)(ksc + 8 * c); k1 = *(const f32x4*)(ksc + 8 * c + 4); }
; #pragma unroll
;     for (int j = 0; j < 4; ++j) { const int n = (lane >> 3) + 8 * j; const LAS float* s = scr + (8 * c) * 33 + n;
;         u32x4 o; o.x = cvt_pk_bf16(s[0 * 33] * k0[0], s[1 * 33] * k0[1]); o.y = cvt_pk_bf16(s[2 * 33] * k0[2], s[3 * 33] * k0[3]);
;         o.z = cvt_pk_bf16(s[4 * 33] * k1[0], s[5 * 33] * k1[1]); o.w = cvt_pk_bf16(s[6 * 33] * k1[2], s[7 * 33] * k1[3]);
;         *(u32x4*)(dst + (size_t)n * ldd + 8 * c) = o; }
; __global__ void __launch_bounds__(NTHR, 2) hybrid_block_fwd(Args a) {
;     ...
;             if (r < I_PP) { const int kb = r / (D / 32), nb = r % (D / 32); tr_tile(w_pool_proj + (size_t)kb * 64 * D + nb * 32, D, nullptr, WT_CAT + (size_t)nb * 32 * KC + kb * 64, KC, scr, lane); continue; } r -= I_PP;
.LBB0_48:
	s_andn2_b64 vcc, exec, s[8:9]
	s_cbranch_vccnz .LBB0_50
	s_and_b32 s6, s18, 0x3fc0
	s_addk_i32 s6, 0xdc00
	s_and_b32 s10, s18, 63
	s_lshl_b64 s[8:9], s[6:7], 13
	s_add_u32 s8, s46, s8
	s_addc_u32 s9, s47, s9
	s_lshl_b32 s11, s10, 7
	s_add_u32 s8, s8, s11
	s_addc_u32 s9, s9, 0
	v_lshlrev_b32_e32 v0, 2, v10
	v_lshlrev_b32_e32 v1, 2, v14
	v_lshlrev_b32_e32 v2, 2, v18
	v_lshlrev_b32_e32 v3, 2, v22
	v_lshlrev_b32_e32 v4, 2, v26
	v_lshlrev_b32_e32 v5, 2, v30
	v_lshlrev_b32_e32 v6, 2, v34
	v_lshlrev_b32_e32 v7, 2, v38
	v_lshlrev_b32_e32 v89, 2, v42
	v_lshlrev_b32_e32 v91, 2, v46
	v_lshlrev_b32_e32 v93, 2, v50
	v_lshlrev_b32_e32 v95, 2, v54
	v_lshlrev_b32_e32 v97, 2, v58
	v_lshlrev_b32_e32 v99, 2, v62
	v_lshlrev_b32_e32 v101, 2, v66
	v_lshlrev_b32_e32 v103, 2, v70
	global_load_dword v0, v0, s[8:9] nt
	s_nop 0
	global_load_dword v1, v1, s[8:9] nt
	s_nop 0
	global_load_dword v2, v2, s[8:9] nt
	s_nop 0
	global_load_dword v3, v3, s[8:9] nt
	s_nop 0
	global_load_dword v4, v4, s[8:9] nt
	s_nop 0
	global_load_dword v5, v5, s[8:9] nt
	s_nop 0
	global_load_dword v6, v6, s[8:9] nt
	s_nop 0
	global_load_dword v7, v7, s[8:9] nt
	s_nop 0
	global_load_dword v89, v89, s[8:9] nt
	s_nop 0
	global_load_dword v91, v91, s[8:9] nt
	s_nop 0
	global_load_dword v93, v93, s[8:9] nt
	s_nop 0
	global_load_dword v95, v95, s[8:9] nt
	s_nop 0
	global_load_dword v97, v97, s[8:9] nt
	s_nop 0
	global_load_dword v99, v99, s[8:9] nt
	s_nop 0
	global_load_dword v101, v101, s[8:9] nt
	s_nop 0
	global_load_dword v103, v103, s[8:9] nt
	v_lshlrev_b32_e32 v105, 2, v74
	v_lshlrev_b32_e32 v107, 2, v78
	v_lshlrev_b32_e32 v109, 2, v82
	v_lshlrev_b32_e32 v111, 2, v86
	v_lshlrev_b32_e32 v113, 2, v90
	v_lshlrev_b32_e32 v115, 2, v94
	v_lshlrev_b32_e32 v117, 2, v98
	v_lshlrev_b32_e32 v119, 2, v102
	global_load_dword v105, v105, s[8:9] nt
	s_nop 0
	global_load_dword v107, v107, s[8:9] nt
	s_nop 0
	global_load_dword v109, v109, s[8:9] nt
	s_nop 0
	global_load_dword v111, v111, s[8:9] nt
	s_nop 0
	global_load_dword v113, v113, s[8:9] nt
	s_nop 0
	global_load_dword v115, v115, s[8:9] nt
	s_nop 0
	global_load_dword v117, v117, s[8:9] nt
	s_nop 0
	global_load_dword v119, v119, s[8:9] nt
	v_lshlrev_b32_e32 v121, 2, v106
	v_lshlrev_b32_e32 v123, 2, v110
	v_lshlrev_b32_e32 v125, 2, v114
	v_lshlrev_b32_e32 v127, 2, v118
	v_lshlrev_b32_e32 v129, 2, v122
	v_lshlrev_b32_e32 v131, 2, v126
	v_lshlrev_b32_e32 v133, 2, v130
	v_lshlrev_b32_e32 v135, 2, v134
	global_load_dword v121, v121, s[8:9] nt
	s_nop 0
	global_load_dword v123, v123, s[8:9] nt
	s_nop 0
	global_load_dword v125, v125, s[8:9] nt
	s_nop 0
	global_load_dword v127, v127, s[8:9] nt
	s_nop 0
	global_load_dword v129, v129, s[8:9] nt
	s_nop 0
	global_load_dword v131, v131, s[8:9] nt
	s_nop 0
	global_load_dword v133, v133, s[8:9] nt
	s_nop 0
	global_load_dword v135, v135, s[8:9] nt
	v_add_u32_e32 v136, v85, v87
	v_add_u32_e32 v139, v85, v11
	v_add_u32_e32 v141, v85, v13
	v_add_u32_e32 v143, 0x400, v136
	v_add_u32_e32 v145, 0x400, v139
	v_add_u32_e32 v147, 0x400, v141
	s_mul_i32 s10, s10, 0x30000
	v_readlane_b32 s2, v248, 32
	s_add_u32 s10, s2, s10
	v_readlane_b32 s2, v248, 33
	s_addc_u32 s11, s2, 0
	s_lshl_b64 s[8:9], s[6:7], 1
	s_add_u32 s8, s10, s8
	s_addc_u32 s9, s11, s9
	s_waitcnt vmcnt(30)
	ds_write2_b32 v136, v0, v1 offset1:66
	s_waitcnt vmcnt(28)
	ds_write2_b32 v136, v2, v3 offset0:132 offset1:198
	s_waitcnt vmcnt(26)
	ds_write2_b32 v143, v4, v5 offset0:8 offset1:74
	s_waitcnt vmcnt(24)
	ds_write2_b32 v139, v6, v7 offset1:66
	s_waitcnt vmcnt(22)
	ds_write2_b32 v139, v89, v91 offset0:132 offset1:198
	s_waitcnt vmcnt(20)
	ds_write2_b32 v145, v93, v95 offset0:8 offset1:74
	s_waitcnt vmcnt(18)
	ds_write2_b32 v141, v97, v99 offset1:66
	s_waitcnt vmcnt(16)
	ds_write2_b32 v141, v101, v103 offset0:132 offset1:198
	s_waitcnt vmcnt(14)
	ds_write2_b32 v147, v105, v107 offset0:8 offset1:74
	v_add_u32_e32 v0, v85, v15
	s_waitcnt vmcnt(12)
	ds_write2_b32 v0, v109, v111 offset1:66
	s_waitcnt vmcnt(10)
	ds_write2_b32 v0, v113, v115 offset0:132 offset1:198
	v_add_u32_e32 v0, 0x400, v0
	s_waitcnt vmcnt(8)
	ds_write2_b32 v0, v117, v119 offset0:8 offset1:74
	v_add_u32_e32 v0, v85, v83
	s_waitcnt vmcnt(6)
	ds_write2_b32 v0, v121, v123 offset1:66
	s_waitcnt vmcnt(4)
	ds_write2_b32 v0, v125, v127 offset0:132 offset1:198
	v_add_u32_e32 v0, 0x400, v0
	s_waitcnt vmcnt(2)
	ds_write2_b32 v0, v129, v131 offset0:8 offset1:74
	s_waitcnt vmcnt(0)
	ds_write2_b32 v0, v133, v135 offset0:140 offset1:206
	s_waitcnt lgkmcnt(0)
	ds_read2_b32 v[0:1], v17 offset1:33
	s_waitcnt lgkmcnt(0)
	v_cvt_pk_bf16_f32 v0, v0, v1
	ds_read2_b32 v[2:3], v17 offset0:66 offset1:99
	v_lshlrev_b32_e32 v136, 1, v138
	s_waitcnt lgkmcnt(0)
	v_cvt_pk_bf16_f32 v1, v2, v3
	ds_read2_b32 v[2:3], v17 offset0:132 offset1:165
	v_lshl_add_u64 v[6:7], s[8:9], 0, v[136:137]
	v_lshlrev_b32_e32 v136, 1, v156
	s_waitcnt lgkmcnt(0)
	v_cvt_pk_bf16_f32 v2, v2, v3
	ds_read2_b32 v[4:5], v17 offset0:198 offset1:231
	s_waitcnt lgkmcnt(0)
	v_cvt_pk_bf16_f32 v3, v4, v5
	v_lshl_add_u64 v[6:7], v[6:7], 0, v[136:137]
	ds_read2_b32 v[4:5], v17 offset0:8 offset1:41
	global_store_dwordx4 v[6:7], v[0:3], off
	v_add_co_u32_e32 v160, vcc, s14, v6
	s_waitcnt lgkmcnt(0)
	v_cvt_pk_bf16_f32 v0, v4, v5
	ds_read2_b32 v[2:3], v17 offset0:74 offset1:107
	s_waitcnt lgkmcnt(0)
	v_cvt_pk_bf16_f32 v1, v2, v3
	ds_read2_b32 v[2:3], v17 offset0:140 offset1:173
	s_waitcnt lgkmcnt(0)
	v_cvt_pk_bf16_f32 v2, v2, v3
	ds_read2_b32 v[4:5], v17 offset0:206 offset1:239
	s_waitcnt lgkmcnt(0)
	v_cvt_pk_bf16_f32 v3, v4, v5
	v_addc_co_u32_e32 v161, vcc, 0, v7, vcc
	ds_read2_b32 v[4:5], v17 offset0:16 offset1:49
	global_store_dwordx4 v[160:161], v[0:3], off
	v_add_co_u32_e32 v160, vcc, s15, v6
	s_waitcnt lgkmcnt(0)
	v_cvt_pk_bf16_f32 v0, v4, v5
	ds_read2_b32 v[2:3], v17 offset0:82 offset1:115
	s_waitcnt lgkmcnt(0)
	v_cvt_pk_bf16_f32 v1, v2, v3
	ds_read2_b32 v[2:3], v17 offset0:148 offset1:181
	s_waitcnt lgkmcnt(0)
	v_cvt_pk_bf16_f32 v2, v2, v3
	ds_read2_b32 v[4:5], v17 offset0:214 offset1:247
	s_waitcnt lgkmcnt(0)
	v_cvt_pk_bf16_f32 v3, v4, v5
	v_addc_co_u32_e32 v161, vcc, 0, v7, vcc
	ds_read2_b32 v[4:5], v17 offset0:24 offset1:57
	global_store_dwordx4 v[160:161], v[0:3], off
	v_add_co_u32_e32 v6, vcc, 0x24000, v6
	s_waitcnt lgkmcnt(0)
	v_cvt_pk_bf16_f32 v0, v4, v5
	ds_read2_b32 v[2:3], v17 offset0:90 offset1:123
	s_waitcnt lgkmcnt(0)
	v_cvt_pk_bf16_f32 v1, v2, v3
	ds_read2_b32 v[2:3], v17 offset0:156 offset1:189
	v_addc_co_u32_e32 v7, vcc, 0, v7, vcc
	s_waitcnt lgkmcnt(0)
	v_cvt_pk_bf16_f32 v2, v2, v3
	ds_read2_b32 v[4:5], v17 offset0:222 offset1:255
	s_waitcnt lgkmcnt(0)
	v_cvt_pk_bf16_f32 v3, v4, v5
	global_store_dwordx4 v[6:7], v[0:3], off
	s_waitcnt lgkmcnt(0)

; #define LAS __attribute__((address_space(3)))
; #define LDS_WAIT() asm volatile("s_waitcnt lgkmcnt(0)" ::: "memory")
; __device__ __forceinline__ void tr_tile(const float* src, int ldw, const float* ksc, bf16_t* dst, int ldd, LAS float* scr, int lane) {
;     float v[32];
; #pragma unroll
;     for (int i = 0; i < 32; ++i) v[i] = src[(size_t)(2 * i + (lane >> 5)) * ldw + (lane & 31)];
; #pragma unroll
;     for (int i = 0; i < 32; ++i) scr[(2 * i + (lane >> 5)) * 33 + (lane & 31)] = v[i];
;     LDS_WAIT();
;     const int c = lane & 7;
;     f32x4 k0 = (f32x4){1.f, 1.f, 1.f, 1.f}, k1 = k0;
;     if (ksc) { k0 = *(const f32x4*)(ksc + 8 * c); k1 = *(const f32x4*)(ksc + 8 * c + 4); }
; __device__ __forceinline__ void tr_plain(const float* W, int K, int N, const float* ksc, bf16_t* WT, int item, LAS float* scr, int lane) {
;     const int nblk = N / 32, kb = item / nblk, nb = item % nblk, k0 = kb * 64, n0 = nb * 32;
;     tr_tile(W + (size_t)k0 * N + n0, N, ksc ? ksc + k0 : nullptr, WT + (size_t)n0 * K + k0, K, scr, lane);
; __global__ void __launch_bounds__(NTHR, 2) hybrid_block_fwd(Args a) {
;     ...
;             if (r < I_IN) { tr_plain(w_in, D, INW, g_mix, WT_IN, r, scr, lane); continue; } r -= I_IN;
.LBB0_51:
	s_andn2_b64 vcc, exec, s[8:9]
	s_cbranch_vccnz .LBB0_32
	s_mul_hi_i32 s6, s18, 0x38e38e39
	s_lshr_b32 s8, s6, 31
	s_ashr_i32 s6, s6, 6
	s_add_i32 s6, s6, s8
	s_lshl_b32 s8, s6, 6
	s_mul_i32 s9, s6, 0xffffdc00
	s_add_i32 s10, s5, s9
	s_ashr_i32 s9, s8, 31
	s_mul_i32 s6, s6, 0x240000
	s_mul_hi_i32 s11, s8, 0x9000
	s_add_u32 s6, s56, s6
	s_addc_u32 s19, s57, s11
	s_ashr_i32 s11, s10, 31
	s_lshl_b64 s[20:21], s[10:11], 2
	s_add_u32 s20, s6, s20
	s_addc_u32 s21, s19, s21
	global_load_dword v0, v79, s[20:21] nt
	global_load_dword v1, v19, s[20:21] nt
	global_load_dword v2, v21, s[20:21] nt
	global_load_dword v3, v23, s[20:21] nt
	global_load_dword v4, v25, s[20:21] nt
	global_load_dword v5, v27, s[20:21] nt
	global_load_dword v6, v29, s[20:21] nt
	global_load_dword v7, v31, s[20:21] nt
	global_load_dword v89, v33, s[20:21] nt
	global_load_dword v91, v35, s[20:21] nt
	global_load_dword v93, v37, s[20:21] nt
	global_load_dword v95, v39, s[20:21] nt
	global_load_dword v97, v41, s[20:21] nt
	global_load_dword v99, v43, s[20:21] nt
	global_load_dword v101, v45, s[20:21] nt
	global_load_dword v103, v47, s[20:21] nt
	global_load_dword v105, v49, s[20:21] nt
	global_load_dword v107, v51, s[20:21] nt
	global_load_dword v109, v53, s[20:21] nt
	global_load_dword v111, v55, s[20:21] nt
	global_load_dword v113, v57, s[20:21] nt
	global_load_dword v115, v59, s[20:21] nt
	global_load_dword v117, v61, s[20:21] nt
	global_load_dword v119, v63, s[20:21] nt
	global_load_dword v121, v65, s[20:21] nt
	global_load_dword v123, v67, s[20:21] nt
	global_load_dword v125, v69, s[20:21] nt
	global_load_dword v127, v71, s[20:21] nt
	global_load_dword v129, v73, s[20:21] nt
	global_load_dword v131, v75, s[20:21] nt
	global_load_dword v133, v77, s[20:21] nt
	global_load_dword v135, v81, s[20:21] nt
	v_add_u32_e32 v136, v85, v87
	v_add_u32_e32 v139, v85, v11
	v_add_u32_e32 v141, v85, v13
	v_add_u32_e32 v143, v85, v15
	v_add_u32_e32 v145, v85, v83
	v_add_u32_e32 v147, 0x400, v136
	v_add_u32_e32 v149, 0x400, v139
	v_add_u32_e32 v151, 0x400, v141
	v_add_u32_e32 v153, 0x400, v143
	v_add_u32_e32 v155, 0x400, v145
	s_andn2_b64 vcc, exec, s[0:1]
	s_waitcnt vmcnt(30)
	ds_write2_b32 v136, v0, v1 offset1:66
	s_waitcnt vmcnt(28)
	ds_write2_b32 v136, v2, v3 offset0:132 offset1:198
	s_waitcnt vmcnt(26)
	ds_write2_b32 v147, v4, v5 offset0:8 offset1:74
	s_waitcnt vmcnt(24)
	ds_write2_b32 v139, v6, v7 offset1:66
	s_waitcnt vmcnt(22)
	ds_write2_b32 v139, v89, v91 offset0:132 offset1:198
	s_waitcnt vmcnt(20)
	ds_write2_b32 v149, v93, v95 offset0:8 offset1:74
	s_waitcnt vmcnt(18)
	ds_write2_b32 v141, v97, v99 offset1:66
	s_waitcnt vmcnt(16)
	ds_write2_b32 v141, v101, v103 offset0:132 offset1:198
	s_waitcnt vmcnt(14)
	ds_write2_b32 v151, v105, v107 offset0:8 offset1:74
	s_waitcnt vmcnt(12)
	ds_write2_b32 v143, v109, v111 offset1:66
	s_waitcnt vmcnt(10)
	ds_write2_b32 v143, v113, v115 offset0:132 offset1:198
	s_waitcnt vmcnt(8)
	ds_write2_b32 v153, v117, v119 offset0:8 offset1:74
	s_waitcnt vmcnt(6)
	ds_write2_b32 v145, v121, v123 offset1:66
	s_waitcnt vmcnt(4)
	ds_write2_b32 v145, v125, v127 offset0:132 offset1:198
	s_waitcnt vmcnt(2)
	ds_write2_b32 v155, v129, v131 offset0:8 offset1:74
	s_waitcnt vmcnt(0)
	ds_write2_b32 v155, v133, v135 offset0:140 offset1:206
	s_waitcnt lgkmcnt(0)
	s_cbranch_vccz .LBB0_30
	v_mov_b32_e32 v4, 1.0
	v_mov_b32_e32 v5, 1.0
	v_mov_b32_e32 v6, 1.0
	v_mov_b32_e32 v7, 1.0
	v_mov_b32_e32 v0, 1.0
	v_mov_b32_e32 v1, 1.0
	v_mov_b32_e32 v2, 1.0
	v_mov_b32_e32 v3, 1.0
	s_branch .LBB0_31

; __global__ void __launch_bounds__(NTHR, 2) hybrid_block_fwd(Args a) {
;     ...
;             const f32x4* xr = (const f32x4*)(x + (size_t)row * D) + lane; f32x4 v[8]; float s = 0.f;
; #pragma unroll
;             for (int j = 0; j < 8; ++j) { v[j] = xr[64 * j]; s += (v[j][0] * v[j][0] + v[j][1] * v[j][1]) + (v[j][2] * v[j][2] + v[j][3] * v[j][3]); }
;             s = wave_sum(s);
;             const float nrm1 = sqrtf(s * (1.0f / D) + EPS), rs1 = 1.0f / nrm1;
;             if (lane == 0) RSTD1[row] = nrm1;
.LBB0_57:
	v_add_co_u32_e32 v16, vcc, 0xfffff000, v36
	global_load_dwordx4 v[0:3], v[36:37], off offset:-3072 nt
	global_load_dwordx4 v[4:7], v[36:37], off offset:-2048 nt
	global_load_dwordx4 v[8:11], v[36:37], off offset:-1024 nt
	global_load_dwordx4 v[12:15], v[36:37], off nt
	v_addc_co_u32_e32 v17, vcc, -1, v37, vcc
	global_load_dwordx4 v[28:31], v[16:17], off offset:-3072 nt
	global_load_dwordx4 v[24:27], v[16:17], off offset:-2048 nt
	global_load_dwordx4 v[20:23], v[16:17], off offset:-1024 nt
	s_nop 0
	global_load_dwordx4 v[16:19], v[36:37], off offset:-4096 nt
	s_waitcnt vmcnt(7)
	v_mul_f32_e32 v46, v1, v1
	v_mul_f32_e32 v47, v3, v3
	s_waitcnt vmcnt(6)
	v_mul_f32_e32 v48, v5, v5
	v_mul_f32_e32 v49, v7, v7
	s_waitcnt vmcnt(5)
	v_mul_f32_e32 v50, v9, v9
	v_mul_f32_e32 v51, v11, v11
	s_waitcnt vmcnt(3)
	v_mul_f32_e32 v54, v29, v29
	v_mul_f32_e32 v55, v31, v31
	s_waitcnt vmcnt(2)
	v_mul_f32_e32 v56, v25, v25
	v_mul_f32_e32 v57, v27, v27
	v_mul_f32_e32 v52, v13, v13
	v_mul_f32_e32 v53, v15, v15
	v_fmac_f32_e32 v46, v0, v0
	v_fmac_f32_e32 v47, v2, v2
	v_fmac_f32_e32 v48, v4, v4
	v_fmac_f32_e32 v49, v6, v6
	v_fmac_f32_e32 v50, v8, v8
	v_fmac_f32_e32 v51, v10, v10
	s_waitcnt vmcnt(1)
	v_mul_f32_e32 v58, v21, v21
	v_mul_f32_e32 v59, v23, v23
	v_fmac_f32_e32 v54, v28, v28
	v_fmac_f32_e32 v55, v30, v30
	v_fmac_f32_e32 v56, v24, v24
	v_fmac_f32_e32 v57, v26, v26
	v_fmac_f32_e32 v52, v12, v12
	v_fmac_f32_e32 v53, v14, v14
	s_waitcnt vmcnt(0)
	v_mul_f32_e32 v60, v17, v17
	v_mul_f32_e32 v61, v19, v19
	v_add_f32_e32 v46, v46, v47
	v_add_f32_e32 v47, v48, v49
	v_add_f32_e32 v48, v50, v51
	v_fmac_f32_e32 v58, v20, v20
	v_fmac_f32_e32 v59, v22, v22
	v_add_f32_e32 v50, v54, v55
	v_add_f32_e32 v51, v56, v57
	v_add_f32_e32 v49, v52, v53
	v_fmac_f32_e32 v60, v16, v16
	v_fmac_f32_e32 v61, v18, v18
	v_add_f32_e32 v52, v58, v59
	v_add_f32_e32 v50, v50, v51
	v_add_f32_e32 v53, v60, v61
	v_add_f32_e32 v50, v50, v52
	v_add_f32_e32 v50, v50, v53
	v_add_f32_e32 v46, v50, v46
	v_add_f32_e32 v46, v46, v47
	v_add_f32_e32 v46, v46, v48
	v_add_f32_e32 v46, v46, v49
	ds_bpermute_b32 v47, v39, v46
	s_waitcnt lgkmcnt(0)
	v_add_f32_e32 v46, v46, v47
	ds_bpermute_b32 v47, v40, v46
	s_waitcnt lgkmcnt(0)
	v_add_f32_e32 v46, v46, v47
	ds_bpermute_b32 v47, v41, v46
	s_waitcnt lgkmcnt(0)
	v_add_f32_e32 v46, v46, v47
	ds_bpermute_b32 v47, v42, v46
	s_waitcnt lgkmcnt(0)
	v_add_f32_e32 v46, v46, v47
	ds_bpermute_b32 v47, v43, v46
	s_waitcnt lgkmcnt(0)
	v_add_f32_e32 v46, v46, v47
	ds_bpermute_b32 v47, v44, v46
	s_waitcnt lgkmcnt(0)
	v_add_f32_e32 v46, v46, v47
	v_fmamk_f32 v46, v46, 0x3a000000, v34
	v_mul_f32_e32 v47, 0x4f800000, v46
	v_cmp_gt_f32_e32 vcc, s13, v46
	s_nop 1
	v_cndmask_b32_e32 v46, v46, v47, vcc
	v_sqrt_f32_e32 v47, v46
	s_nop 0
	v_add_u32_e32 v48, -1, v47
	v_add_u32_e32 v49, 1, v47
	v_fma_f32 v50, -v48, v47, v46
	v_fma_f32 v51, -v49, v47, v46
	v_cmp_ge_f32_e64 s[4:5], 0, v50
	s_nop 1
	v_cndmask_b32_e64 v47, v47, v48, s[4:5]
	v_cmp_lt_f32_e64 s[4:5], 0, v51
	s_nop 1
	v_cndmask_b32_e64 v47, v47, v49, s[4:5]
	v_mul_f32_e32 v48, 0x37800000, v47
	v_cndmask_b32_e32 v47, v47, v48, vcc
	v_cmp_class_f32_e32 vcc, v46, v45
	s_nop 1
	v_cndmask_b32_e32 v46, v47, v46, vcc
	s_and_saveexec_b64 s[4:5], s[0:1]
	s_cbranch_execz .LBB0_56
	s_add_u32 s18, s94, s6
	s_addc_u32 s19, s95, s7
	global_store_dword v35, v46, s[18:19]
	s_branch .LBB0_56

; #define LAS __attribute__((address_space(3)))
; __device__ __forceinline__ unsigned cvt_pk_bf16(float lo, float hi) { unsigned r; asm volatile("v_cvt_pk_bf16_f32 %0, %1, %2" : "=v"(r) : "v"(lo), "v"(hi)); return r; }
; #define LDS_WAIT() asm volatile("s_waitcnt lgkmcnt(0)" ::: "memory")
; __device__ __forceinline__ void tr_tile(const float* src, int ldw, const float* ksc, bf16_t* dst, int ldd, LAS float* scr, int lane) {
;     float v[32];
; #pragma unroll
;     for (int i = 0; i < 32; ++i) v[i] = src[(size_t)(2 * i + (lane >> 5)) * ldw + (lane & 31)];
; #pragma unroll
;     for (int i = 0; i < 32; ++i) scr[(2 * i + (lane >> 5)) * 33 + (lane & 31)] = v[i];
;     LDS_WAIT();
;     const int c = lane & 7;
;     f32x4 k0 = (f32x4){1.f, 1.f, 1.f, 1.f}, k1 = k0;
;     if (ksc) { k0 = *(const f32x4*)(ksc + 8 * c); k1 = *(const f32x4*)(ksc + 8 * c + 4); }
; #pragma unroll
;     for (int j = 0; j < 4; ++j) { const int n = (lane >> 3) + 8 * j; const LAS float* s = scr + (8 * c) * 33 + n;
;         u32x4 o; o.x = cvt_pk_bf16(s[0 * 33] * k0[0], s[1 * 33] * k0[1]); o.y = cvt_pk_bf16(s[2 * 33] * k0[2], s[3 * 33] * k0[3]);
;         o.z = cvt_pk_bf16(s[4 * 33] * k1[0], s[5 * 33] * k1[1]); o.w = cvt_pk_bf16(s[6 * 33] * k1[2], s[7 * 33] * k1[3]);
;         *(u32x4*)(dst + (size_t)n * ldd + 8 * c) = o; }
; __device__ __forceinline__ void tr_plain(const float* W, int K, int N, const float* ksc, bf16_t* WT, int item, LAS float* scr, int lane) {
;     const int nblk = N / 32, kb = item / nblk, nb = item % nblk, k0 = kb * 64, n0 = nb * 32;
;     tr_tile(W + (size_t)k0 * N + n0, N, ksc ? ksc + k0 : nullptr, WT + (size_t)n0 * K + k0, K, scr, lane);
; __global__ void __launch_bounds__(NTHR, 2) hybrid_block_fwd(Args a) {
;     ...
;             } else tr_plain(w_down, FF, D, nullptr, WT_DOWN, it - I_UP, scr, lane);
.LBB0_857:
	s_mov_b64 s[4:5], -1
	s_cmpk_gt_i32 s8, 0x2fff
	v_add_u32_e32 v5, 0x400, v88
	v_add_u32_e32 v4, 0x400, v89
	v_add_u32_e32 v3, 0x400, v90
	v_add_u32_e32 v2, 0x800, v90
	v_add_u32_e32 v1, 0xc00, v90
	v_add_u32_e32 v0, 0x1000, v90
	v_lshlrev_b32_e32 v8, 1, v10
	s_cbranch_scc0 .LBB0_859
	s_add_i32 s4, s8, 0xd000
	s_and_b32 s6, s4, 0xffc0
	s_and_b32 s7, s11, 0x7e0
	s_lshl_b32 s4, s6, 13
	s_add_u32 s4, s88, s4
	s_addc_u32 s5, s89, 0
	s_lshl_b32 s13, s7, 2
	s_add_u32 s4, s4, s13
	s_addc_u32 s5, s5, 0
	global_load_dword v6, v24, s[4:5] nt
	global_load_dword v7, v25, s[4:5] nt
	global_load_dword v15, v26, s[4:5] nt
	global_load_dword v17, v27, s[4:5] nt
	global_load_dword v19, v28, s[4:5] nt
	global_load_dword v21, v29, s[4:5] nt
	global_load_dword v23, v30, s[4:5] nt
	global_load_dword v91, v31, s[4:5] nt
	global_load_dword v92, v32, s[4:5] nt
	global_load_dword v93, v33, s[4:5] nt
	global_load_dword v94, v34, s[4:5] nt
	global_load_dword v95, v35, s[4:5] nt
	global_load_dword v96, v36, s[4:5] nt
	global_load_dword v97, v37, s[4:5] nt
	global_load_dword v98, v38, s[4:5] nt
	global_load_dword v99, v39, s[4:5] nt
	global_load_dword v100, v40, s[4:5] nt
	global_load_dword v101, v41, s[4:5] nt
	global_load_dword v102, v42, s[4:5] nt
	global_load_dword v103, v43, s[4:5] nt
	global_load_dword v104, v44, s[4:5] nt
	global_load_dword v105, v45, s[4:5] nt
	global_load_dword v106, v46, s[4:5] nt
	global_load_dword v107, v47, s[4:5] nt
	global_load_dword v108, v48, s[4:5] nt
	global_load_dword v109, v49, s[4:5] nt
	global_load_dword v110, v50, s[4:5] nt
	global_load_dword v111, v51, s[4:5] nt
	global_load_dword v112, v52, s[4:5] nt
	global_load_dword v113, v53, s[4:5] nt
	global_load_dword v114, v54, s[4:5] nt
	global_load_dword v115, v55, s[4:5] nt
	s_mulk_i32 s7, 0x3000
	s_add_u32 s4, s27, s7
	s_addc_u32 s5, s28, 0
	s_lshl_b32 s6, s6, 1
	s_add_u32 s4, s4, s6
	s_addc_u32 s5, s5, 0
	s_waitcnt vmcnt(30)
	ds_write2_b32 v88, v6, v7 offset1:66
	s_waitcnt vmcnt(28)
	ds_write2_b32 v88, v15, v17 offset0:132 offset1:198
	s_waitcnt vmcnt(26)
	ds_write2_b32 v5, v19, v21 offset0:8 offset1:74
	s_waitcnt vmcnt(24)
	ds_write2_b32 v89, v23, v91 offset1:66
	s_waitcnt vmcnt(22)
	ds_write2_b32 v89, v92, v93 offset0:132 offset1:198
	s_waitcnt vmcnt(20)
	ds_write2_b32 v4, v94, v95 offset0:8 offset1:74
	s_waitcnt vmcnt(18)
	ds_write2_b32 v90, v96, v97 offset1:66
	s_waitcnt vmcnt(16)
	ds_write2_b32 v90, v98, v99 offset0:132 offset1:198
	s_waitcnt vmcnt(14)
	ds_write2_b32 v3, v100, v101 offset0:8 offset1:74
	s_waitcnt vmcnt(12)
	ds_write2_b32 v3, v102, v103 offset0:140 offset1:206
	s_waitcnt vmcnt(10)
	ds_write2_b32 v2, v104, v105 offset0:16 offset1:82
	s_waitcnt vmcnt(8)
	ds_write2_b32 v2, v106, v107 offset0:148 offset1:214
	s_waitcnt vmcnt(6)
	ds_write2_b32 v1, v108, v109 offset0:24 offset1:90
	s_waitcnt vmcnt(4)
	ds_write2_b32 v1, v110, v111 offset0:156 offset1:222
	s_waitcnt vmcnt(2)
	ds_write2_b32 v0, v112, v113 offset0:32 offset1:98
	s_waitcnt vmcnt(0)
	ds_write2_b32 v0, v114, v115 offset0:164 offset1:230
	s_waitcnt lgkmcnt(0)
	ds_read2_b32 v[6:7], v11 offset1:33
	s_waitcnt lgkmcnt(0)
	v_cvt_pk_bf16_f32 v92, v6, v7
	ds_read2_b32 v[6:7], v11 offset0:66 offset1:99
	s_waitcnt lgkmcnt(0)
	v_cvt_pk_bf16_f32 v93, v6, v7
	ds_read2_b32 v[6:7], v11 offset0:132 offset1:165
	v_mov_b32_e32 v15, v9
	s_waitcnt lgkmcnt(0)
	v_cvt_pk_bf16_f32 v94, v6, v7
	ds_read2_b32 v[6:7], v11 offset0:198 offset1:231
	v_lshl_add_u64 v[96:97], s[4:5], 0, v[8:9]
	s_waitcnt lgkmcnt(0)
	v_cvt_pk_bf16_f32 v95, v6, v7
	ds_read2_b32 v[6:7], v11 offset0:8 offset1:41
	v_lshl_add_u64 v[96:97], v[96:97], 0, v[14:15]
	global_store_dwordx4 v[96:97], v[92:95], off
	v_add_co_u32_e32 v98, vcc, s9, v96
	s_waitcnt lgkmcnt(0)
	v_cvt_pk_bf16_f32 v92, v6, v7
	ds_read2_b32 v[6:7], v11 offset0:74 offset1:107
	s_waitcnt lgkmcnt(0)
	v_cvt_pk_bf16_f32 v93, v6, v7
	ds_read2_b32 v[6:7], v11 offset0:140 offset1:173
	s_waitcnt lgkmcnt(0)
	v_cvt_pk_bf16_f32 v94, v6, v7
	ds_read2_b32 v[6:7], v11 offset0:206 offset1:239
	s_waitcnt lgkmcnt(0)
	v_cvt_pk_bf16_f32 v95, v6, v7
	ds_read2_b32 v[6:7], v11 offset0:16 offset1:49
	v_addc_co_u32_e32 v99, vcc, 0, v97, vcc
	global_store_dwordx4 v[98:99], v[92:95], off
	v_add_co_u32_e32 v98, vcc, s10, v96
	s_waitcnt lgkmcnt(0)
	v_cvt_pk_bf16_f32 v92, v6, v7
	ds_read2_b32 v[6:7], v11 offset0:82 offset1:115
	s_waitcnt lgkmcnt(0)
	v_cvt_pk_bf16_f32 v93, v6, v7
	ds_read2_b32 v[6:7], v11 offset0:148 offset1:181
	s_waitcnt lgkmcnt(0)
	v_cvt_pk_bf16_f32 v94, v6, v7
	ds_read2_b32 v[6:7], v11 offset0:214 offset1:247
	s_waitcnt lgkmcnt(0)
	v_cvt_pk_bf16_f32 v95, v6, v7
	ds_read2_b32 v[6:7], v11 offset0:24 offset1:57
	v_addc_co_u32_e32 v99, vcc, 0, v97, vcc
	global_store_dwordx4 v[98:99], v[92:95], off
	v_add_co_u32_e32 v96, vcc, 0x48000, v96
	s_waitcnt lgkmcnt(0)
	v_cvt_pk_bf16_f32 v92, v6, v7
	ds_read2_b32 v[6:7], v11 offset0:90 offset1:123
	s_waitcnt lgkmcnt(0)
	v_cvt_pk_bf16_f32 v93, v6, v7
	ds_read2_b32 v[6:7], v11 offset0:156 offset1:189
	v_addc_co_u32_e32 v97, vcc, 0, v97, vcc
	s_waitcnt lgkmcnt(0)
	v_cvt_pk_bf16_f32 v94, v6, v7
	ds_read2_b32 v[6:7], v11 offset0:222 offset1:255
	s_waitcnt lgkmcnt(0)
	v_cvt_pk_bf16_f32 v95, v6, v7
	global_store_dwordx4 v[96:97], v[92:95], off
	s_waitcnt lgkmcnt(0)
	s_mov_b64 s[4:5], 0
; #define LDS_WAIT() asm volatile("s_waitcnt lgkmcnt(0)" ::: "memory")
; __device__ __forceinline__ void tr_tile(const float* src, int ldw, const float* ksc, bf16_t* dst, int ldd, LAS float* scr, int lane) {
;     float v[32];
; #pragma unroll
;     for (int i = 0; i < 32; ++i) v[i] = src[(size_t)(2 * i + (lane >> 5)) * ldw + (lane & 31)];
; #pragma unroll
;     for (int i = 0; i < 32; ++i) scr[(2 * i + (lane >> 5)) * 33 + (lane & 31)] = v[i];
;     LDS_WAIT();
;     const int c = lane & 7;
;     f32x4 k0 = (f32x4){1.f, 1.f, 1.f, 1.f}, k1 = k0;
;     if (ksc) { k0 = *(const f32x4*)(ksc + 8 * c); k1 = *(const f32x4*)(ksc + 8 * c + 4); }
; __global__ void __launch_bounds__(NTHR, 2) hybrid_block_fwd(Args a) {
;     ...
;                 const int nblk = 2 * FF / 32, kb = it / nblk, nb = it % nblk, n0 = nb * 32, pn = n0 >> 8, bj = (n0 >> 7) & 1, j0 = n0 & 127, k0 = kb * 64;
;                 tr_tile(w_up + (size_t)k0 * (2 * FF) + bj * FF + pn * 128 + j0, 2 * FF, g_mlp + k0, WT_UP + (size_t)n0 * D + k0, D, scr, lane);
.LBB0_859:
	s_andn2_b64 vcc, exec, s[4:5]
	s_cbranch_vccnz .LBB0_856
	s_mul_hi_i32 s4, s8, 0x2aaaaaab
	s_lshr_b32 s5, s4, 31
	s_ashr_i32 s4, s4, 6
	s_add_i32 s7, s4, s5
	s_mul_i32 s4, s7, 0xffffd000
	s_add_i32 s6, s11, s4
	s_lshl_b32 s4, s7, 6
	s_and_b32 s13, s6, 0x60
	s_ashr_i32 s5, s4, 31
	s_mul_i32 s14, s7, 0x300000
	s_mul_hi_i32 s15, s4, 0xc000
	s_add_u32 s14, s82, s14
	s_addc_u32 s15, s83, s15
	s_bfe_i32 s16, s8, 0x10002
	s_and_b32 s16, s16, 0x6000
	s_add_u32 s16, s14, s16
	s_mulk_i32 s7, 0xe800
	s_addc_u32 s17, s15, 0
	s_add_i32 s7, s12, s7
	s_and_b32 s14, s7, 0xffffff80
	s_ashr_i32 s15, s14, 31
	s_lshl_b64 s[14:15], s[14:15], 2
	s_add_u32 s7, s16, s14
	s_addc_u32 s15, s17, s15
	s_lshl_b32 s13, s13, 2
	s_add_u32 s14, s7, s13
	s_addc_u32 s15, s15, 0
	global_load_dword v6, v56, s[14:15] nt
	global_load_dword v7, v57, s[14:15] nt
	global_load_dword v15, v58, s[14:15] nt
	global_load_dword v17, v59, s[14:15] nt
	global_load_dword v19, v60, s[14:15] nt
	global_load_dword v21, v61, s[14:15] nt
	global_load_dword v23, v62, s[14:15] nt
	global_load_dword v91, v63, s[14:15] nt
	global_load_dword v92, v64, s[14:15] nt
	global_load_dword v93, v65, s[14:15] nt
	global_load_dword v94, v66, s[14:15] nt
	global_load_dword v95, v67, s[14:15] nt
	global_load_dword v96, v68, s[14:15] nt
	global_load_dword v97, v69, s[14:15] nt
	global_load_dword v98, v70, s[14:15] nt
	global_load_dword v99, v71, s[14:15] nt
	global_load_dword v100, v72, s[14:15] nt
	global_load_dword v101, v73, s[14:15] nt
	global_load_dword v102, v74, s[14:15] nt
	global_load_dword v103, v75, s[14:15] nt
	global_load_dword v104, v76, s[14:15] nt
	global_load_dword v105, v77, s[14:15] nt
	global_load_dword v106, v78, s[14:15] nt
	global_load_dword v107, v79, s[14:15] nt
	global_load_dword v108, v80, s[14:15] nt
	global_load_dword v109, v81, s[14:15] nt
	global_load_dword v110, v82, s[14:15] nt
	global_load_dword v111, v83, s[14:15] nt
	global_load_dword v112, v84, s[14:15] nt
	global_load_dword v113, v85, s[14:15] nt
	global_load_dword v114, v86, s[14:15] nt
	global_load_dword v115, v87, s[14:15] nt
	s_andn2_b64 vcc, exec, s[0:1]
	s_waitcnt vmcnt(30)
	ds_write2_b32 v88, v6, v7 offset1:66
	s_waitcnt vmcnt(28)
	ds_write2_b32 v88, v15, v17 offset0:132 offset1:198
	s_waitcnt vmcnt(26)
	ds_write2_b32 v5, v19, v21 offset0:8 offset1:74
	s_waitcnt vmcnt(24)
	ds_write2_b32 v89, v23, v91 offset1:66
	s_waitcnt vmcnt(22)
	ds_write2_b32 v89, v92, v93 offset0:132 offset1:198
	s_waitcnt vmcnt(20)
	ds_write2_b32 v4, v94, v95 offset0:8 offset1:74
	s_waitcnt vmcnt(18)
	ds_write2_b32 v90, v96, v97 offset1:66
	s_waitcnt vmcnt(16)
	ds_write2_b32 v90, v98, v99 offset0:132 offset1:198
	s_waitcnt vmcnt(14)
	ds_write2_b32 v3, v100, v101 offset0:8 offset1:74
	s_waitcnt vmcnt(12)
	ds_write2_b32 v3, v102, v103 offset0:140 offset1:206
	s_waitcnt vmcnt(10)
	ds_write2_b32 v2, v104, v105 offset0:16 offset1:82
	s_waitcnt vmcnt(8)
	ds_write2_b32 v2, v106, v107 offset0:148 offset1:214
	s_waitcnt vmcnt(6)
	ds_write2_b32 v1, v108, v109 offset0:24 offset1:90
	s_waitcnt vmcnt(4)
	ds_write2_b32 v1, v110, v111 offset0:156 offset1:222
	s_waitcnt vmcnt(2)
	ds_write2_b32 v0, v112, v113 offset0:32 offset1:98
	s_waitcnt vmcnt(0)
	ds_write2_b32 v0, v114, v115 offset0:164 offset1:230
	s_waitcnt lgkmcnt(0)
	s_cbranch_vccz .LBB0_854
	v_mov_b32_e32 v4, 1.0
	v_mov_b32_e32 v5, 1.0
	v_mov_b32_e32 v6, 1.0
	v_mov_b32_e32 v7, 1.0
	v_mov_b32_e32 v0, 1.0
	v_mov_b32_e32 v1, 1.0
	v_mov_b32_e32 v2, 1.0
	v_mov_b32_e32 v3, 1.0
	s_branch .LBB0_855
